# adds: row-statistics exchanges poll tagged slots directly (no counter round trips; slots zeroed at kernel start), gate/scale/shift vector loads hoisted above the exchanges
# baseline (speedup 1.0000x reference)
_Z6mk_fwd4Args:
	s_load_dwordx2 s[34:35], s[0:1], 0xa0
	s_load_dword s33, s[0:1], 0xb8
	s_load_dwordx8 s[4:11], s[0:1], 0x80
	v_readfirstlane_b32 s60, v0
	s_mov_b32 s89, s2
	s_waitcnt lgkmcnt(0)
	s_mul_i32 s14, s2, 0xc00
	s_add_u32 s12, s34, 0x1b00000
	s_addc_u32 s13, s35, 0
	s_add_u32 s12, s12, s14
	s_addc_u32 s13, s13, 0
	v_mov_b32_e32 v2, 0
	v_mov_b32_e32 v3, 0
	v_mov_b32_e32 v4, 0
	v_mov_b32_e32 v5, 0
	v_lshlrev_b32_e32 v6, 4, v0
	v_cmp_gt_u32_e32 vcc, 0xc0, v0
	s_and_saveexec_b64 s[14:15], vcc
	global_store_dwordx4 v6, v[2:5], s[12:13] sc1
	s_mov_b64 exec, s[14:15]
	v_writelane_b32 v250, s4, 0
	s_nop 1
	v_writelane_b32 v250, s5, 1
	v_writelane_b32 v250, s6, 2
	v_writelane_b32 v250, s7, 3
	v_writelane_b32 v250, s8, 4
	v_writelane_b32 v250, s9, 5
	v_writelane_b32 v250, s10, 6
	v_writelane_b32 v250, s11, 7
	s_add_u32 s4, s0, 0xb8
	s_addc_u32 s5, s1, 0
	s_and_b32 s3, s33, 7
	v_writelane_b32 v250, s4, 8
	s_cmp_lg_u32 s3, 0
	s_nop 0
	v_writelane_b32 v250, s5, 9
	s_cbranch_scc1 .LBB0_2
	s_ashr_i32 s4, s2, 31
	s_lshr_b32 s4, s4, 29
	s_add_i32 s4, s2, s4
	s_and_b32 s5, s4, -8
	s_ashr_i32 s3, s33, 3
	s_sub_i32 s5, s2, s5
	s_mul_i32 s3, s3, s5
	s_ashr_i32 s4, s4, 3
	s_add_i32 s89, s3, s4

.LBB0_590:
	s_or_b64 exec, exec, s[8:9]
	v_and_b32_e32 v190, 31, v0
	s_waitcnt lgkmcnt(0)
	s_barrier
	v_lshl_or_b32 v192, s48, 5, v190
	v_add_u32_e32 v212, s40, v192
	v_cmp_gt_u32_e64 s[8:9], 32, v1
	v_lshl_add_u32 v223, v192, 4, 0
	v_lshl_add_u32 v222, v192, 2, 0
	v_ashrrev_i32_e32 v213, 31, v212
	s_add_u32 s80, s34, 0x1b00000
	s_addc_u32 s81, s35, 0
	s_mov_b32 s82, s16
	s_mov_b32 s83, 0
	v_lshl_add_u64 v[232:233], v[212:213], 4, s[80:81]
	s_ashr_i32 s12, s14, 31
	s_lshr_b32 s12, s12, 29
	s_add_i32 s12, s14, s12
	s_ashr_i32 s12, s12, 3
	s_mul_hi_i32 s13, s12, 0x6000
	s_mulk_i32 s12, 0x6000
	s_add_u32 s12, s52, s12
	s_addc_u32 s13, s53, s13
	v_lshl_add_u64 v[214:215], v[210:211], 2, s[12:13]
	s_mov_b64 s[12:13], 0x2000
	v_lshl_add_u64 v[190:191], v[214:215], 0, s[12:13]
	s_movk_i32 s12, 0x2000
	v_add_co_u32_e32 v192, vcc, s12, v214
	s_nop 1
	v_addc_co_u32_e32 v193, vcc, 0, v215, vcc
	s_mov_b64 s[12:13], 0x2200
	global_load_dwordx4 v[206:209], v[192:193], off
	global_load_dwordx4 v[202:205], v[190:191], off offset:16
	v_lshl_add_u64 v[190:191], v[214:215], 0, s[12:13]
	global_load_dwordx4 v[198:201], v[192:193], off offset:512
	s_nop 0
	global_load_dwordx4 v[190:193], v[190:191], off offset:16
	s_and_saveexec_b64 s[84:85], s[8:9]
	ds_read_b128 v[236:239], v223
	v_lshl_add_u64 v[234:235], s[82:83], 2, v[232:233]
	s_waitcnt lgkmcnt(0)
	v_add_f32_e32 v236, v237, v236
	v_add_f32_e32 v238, v238, v239
	v_add_f32_e32 v236, v236, v238
	v_add_u32_e32 v236, 1, v236
	global_store_dword v[234:235], v236, off sc1
	s_mov_b32 s88, 0
.Lxa_poll:
	global_load_dwordx4 v[236:239], v[232:233], off sc1
	s_waitcnt vmcnt(0)
	v_min_u32_e32 v240, v236, v237
	v_min_u32_e32 v241, v238, v239
	v_min_u32_e32 v240, v240, v241
	v_cmp_eq_u32_e32 vcc, 0, v240
	s_cbranch_vccz .Lxa_got
	s_add_i32 s88, s88, 1
	s_cmp_lt_u32 s88, 0x40000
	s_cbranch_scc0 .Lxa_tmo
	s_sleep 1
	s_branch .Lxa_poll
.Lxa_tmo:
	v_mov_b32_e32 v236, 0x7fc00000
	v_mov_b32_e32 v237, 0
	v_mov_b32_e32 v238, 1
	global_store_dword v237, v238, s[34:35] sc1
	s_branch .Lxa_put
.Lxa_got:
	v_add_u32_e32 v236, -1, v236
	v_add_u32_e32 v237, -1, v237
	v_add_u32_e32 v238, -1, v238
	v_add_u32_e32 v239, -1, v239
	v_add_f32_e32 v236, 0, v236
	v_add_f32_e32 v236, v236, v237
	v_add_f32_e32 v236, v236, v238
	v_add_f32_e32 v236, v236, v239
	v_mov_b32_e32 v237, 0x358637bd
	s_mov_b32 s90, 0xf800000
	v_fmac_f32_e32 v237, 0x3a800000, v236
	v_mul_f32_e32 v236, 0x4f800000, v237
	v_cmp_gt_f32_e32 vcc, s90, v237
	v_mov_b32_e32 v238, 0x260
	s_nop 0
	v_cndmask_b32_e32 v236, v237, v236, vcc
	v_sqrt_f32_e32 v237, v236
	s_nop 0
	v_add_u32_e32 v239, -1, v237
	v_add_u32_e32 v240, 1, v237
	v_fma_f32 v241, -v239, v237, v236
	v_fma_f32 v242, -v240, v237, v236
	v_cmp_ge_f32_e64 s[90:91], 0, v241
	s_nop 1
	v_cndmask_b32_e64 v237, v237, v239, s[90:91]
	v_cmp_lt_f32_e64 s[90:91], 0, v242
	s_nop 1
	v_cndmask_b32_e64 v237, v237, v240, s[90:91]
	v_mul_f32_e32 v239, 0x37800000, v237
	v_cndmask_b32_e32 v237, v237, v239, vcc
	v_cmp_class_f32_e32 vcc, v236, v238
	s_nop 1
	v_cndmask_b32_e32 v236, v237, v236, vcc
	v_div_scale_f32 v237, s[90:91], v236, v236, 1.0
	v_rcp_f32_e32 v238, v237
	v_div_scale_f32 v239, vcc, 1.0, v236, 1.0
	v_fma_f32 v240, -v237, v238, 1.0
	v_fmac_f32_e32 v238, v240, v238
	v_mul_f32_e32 v240, v239, v238
	v_fma_f32 v241, -v237, v240, v239
	v_fmac_f32_e32 v240, v241, v238
	v_fma_f32 v237, -v237, v240, v239
	v_div_fmas_f32 v237, v237, v238, v240
	v_div_fixup_f32 v236, v237, v236, 1.0
.Lxa_put:
	ds_write_b32 v222, v236 offset:8192
	s_or_b64 exec, exec, s[84:85]
	s_mov_b32 s0, 0
	s_waitcnt lgkmcnt(0)
	s_barrier
	v_readfirstlane_b32 s46, v249
	s_nop 3
	s_or_b32 s0, s0, s46
	s_cmp_lg_u32 s0, 0
	s_cselect_b64 s[18:19], -1, 0
	s_cmp_eq_u32 s0, 0
	s_cselect_b64 s[26:27], -1, 0
	s_and_b32 s0, s47, 0xffffff00
	s_add_i32 s0, s0, 0
	v_lshl_add_u32 v224, v219, 2, s0
	v_mov_b32_e32 v216, 0x7fc00000
	s_and_b64 vcc, exec, s[26:27]
	v_mov_b32_e32 v218, 0x7fc00000
	s_cbranch_vccz .LBB0_615
	ds_read_b32 v218, v224 offset:8192

.LBB0_645:
	s_or_b64 exec, exec, s[12:13]
	s_waitcnt lgkmcnt(0)
	s_barrier
	s_mov_b64 s[0:1], 0x4000
	v_lshl_add_u64 v[130:131], v[214:215], 0, s[0:1]
	s_mov_b64 s[0:1], 0x3000
	v_add_co_u32_e32 v134, vcc, 0x4000, v214
	v_lshl_add_u64 v[132:133], v[214:215], 0, s[0:1]
	s_nop 0
	v_addc_co_u32_e32 v135, vcc, 0, v215, vcc
	s_mov_b64 s[0:1], 0x4200
	v_add_co_u32_e32 v138, vcc, 0x3000, v214
	global_load_dwordx4 v[146:149], v[130:131], off offset:16
	global_load_dwordx4 v[150:153], v[132:133], off offset:16
	v_lshl_add_u64 v[130:131], v[214:215], 0, s[0:1]
	s_mov_b64 s[0:1], 0x3200
	v_addc_co_u32_e32 v139, vcc, 0, v215, vcc
	v_lshl_add_u64 v[140:141], v[214:215], 0, s[0:1]
	global_load_dwordx4 v[154:157], v[134:135], off
	s_nop 0
	global_load_dwordx4 v[134:137], v[134:135], off offset:512
	s_nop 0
	global_load_dwordx4 v[158:161], v[138:139], off
	global_load_dwordx4 v[142:145], v[138:139], off offset:512
	s_nop 0
	global_load_dwordx4 v[130:133], v[130:131], off offset:16
	s_nop 0
	global_load_dwordx4 v[138:141], v[140:141], off offset:16
	s_add_u32 s80, s34, 0x1b40000
	s_addc_u32 s81, s35, 0
	s_mov_b32 s82, s16
	s_mov_b32 s83, 0
	v_lshl_add_u64 v[232:233], v[212:213], 4, s[80:81]
	s_and_saveexec_b64 s[84:85], s[8:9]
	ds_read_b128 v[236:239], v223
	v_lshl_add_u64 v[234:235], s[82:83], 2, v[232:233]
	s_waitcnt lgkmcnt(0)
	v_add_f32_e32 v236, v237, v236
	v_add_f32_e32 v238, v238, v239
	v_add_f32_e32 v236, v236, v238
	v_add_u32_e32 v236, 1, v236
	global_store_dword v[234:235], v236, off sc1
	s_mov_b32 s88, 0

.Lxb_put:
	ds_write_b32 v222, v236 offset:8192
	s_or_b64 exec, exec, s[84:85]
	v_mov_b32_e32 v162, 0
	s_waitcnt lgkmcnt(0)
	s_barrier
	s_waitcnt lgkmcnt(0)
	v_cmp_eq_u32_e32 vcc, 0, v162
	s_xor_b64 s[0:1], s[18:19], -1
	s_and_b64 s[8:9], s[0:1], vcc
	v_mov_b32_e32 v164, 0x7fc00000
	s_and_b64 vcc, exec, s[8:9]
	v_lshl_add_u32 v165, v217, 2, 0
	v_mov_b32_e32 v166, 0x7fc00000
	s_cbranch_vccz .LBB0_670
	ds_read_b32 v166, v165 offset:8192

.LBB0_897:
	s_or_b64 exec, exec, s[0:1]
	v_and_b32_e32 v180, 31, v0
	s_waitcnt lgkmcnt(0)
	s_barrier
	v_lshl_or_b32 v184, s28, 5, v180
	v_add_u32_e32 v246, s2, v184
	v_cmp_gt_u32_e64 s[84:85], 32, v1
	v_ashrrev_i32_e32 v247, 31, v246
	v_lshl_add_u32 v243, v184, 4, 0
	v_lshl_add_u32 v244, v184, 2, 0
	s_add_u32 s80, s34, 0x1b80000
	s_addc_u32 s81, s35, 0
	s_mov_b32 s82, s10
	s_mov_b32 s83, 0
	v_lshl_add_u64 v[232:233], v[246:247], 4, s[80:81]
	s_ashr_i32 s0, s29, 31
	s_lshr_b32 s0, s0, 29
	s_add_i32 s0, s29, s0
	s_ashr_i32 s0, s0, 3
	s_mul_hi_i32 s1, s0, 0x6000
	s_mulk_i32 s0, 0x6000
	s_add_u32 s0, s52, s0
	s_addc_u32 s1, s53, s1
	v_lshl_add_u64 v[178:179], v[178:179], 2, s[0:1]
	s_mov_b64 s[0:1], 0x5000
	v_lshl_add_u64 v[182:183], v[178:179], 0, s[0:1]
	s_movk_i32 s0, 0x5000
	v_add_co_u32_e32 v178, vcc, s0, v178
	s_nop 1
	v_addc_co_u32_e32 v179, vcc, 0, v179, vcc
	global_load_dwordx4 v[194:197], v[178:179], off
	s_nop 0
	global_load_dwordx4 v[178:181], v[182:183], off offset:528
	global_load_dwordx4 v[190:193], v[182:183], off offset:16
	s_nop 0
	global_load_dwordx4 v[182:185], v[182:183], off offset:512
	s_and_saveexec_b64 s[86:87], s[84:85]
	ds_read_b128 v[236:239], v243
	v_lshl_add_u64 v[234:235], s[82:83], 2, v[232:233]
	s_waitcnt lgkmcnt(0)
	v_add_f32_e32 v236, v237, v236
	v_add_f32_e32 v238, v238, v239
	v_add_f32_e32 v236, v236, v238
	v_add_u32_e32 v236, 1, v236
	global_store_dword v[234:235], v236, off sc1
	s_mov_b32 s88, 0

.Lxc_put:
	ds_write_b32 v244, v236 offset:8192
	s_or_b64 exec, exec, s[86:87]
	v_mov_b32_e32 v212, 0
	s_waitcnt lgkmcnt(0)
	s_barrier
	s_waitcnt vmcnt(0)
	v_or_b32_e32 v210, v211, v210
	s_waitcnt lgkmcnt(0)
	v_or_b32_e32 v210, v212, v210
	s_lshl_b32 s0, s30, 2
	s_add_i32 s0, s0, 0
	v_cmp_ne_u32_e32 vcc, 0, v210
	v_cmp_eq_u32_e64 s[2:3], 0, v210
	v_lshl_add_u32 v211, v213, 2, s0
	v_mov_b32_e32 v210, 0x7fc00000
	v_mov_b32_e32 v212, 0x7fc00000
	s_cbranch_vccnz .LBB0_922
	ds_read_b32 v212, v211 offset:8192
